# stack + prologue x conversion loop: next row's loads issued right after the current row is converted (guarded at the last row)
# baseline (speedup 1.0000x reference)
.LBB0_57:
	s_or_b64 exec, exec, s[2:3]
	s_load_dword s4, s[0:1], 0x6c
	s_cmp_lt_i32 s64, 0x8000
	s_cselect_b64 s[0:1], -1, 0
	v_writelane_b32 v251, s0, 28
	s_cmpk_gt_i32 s64, 0x7fff
	s_nop 0
	v_writelane_b32 v251, s1, 29
	s_cbranch_scc1 .LBB0_60
	s_ashr_i32 s65, s64, 31
	s_lshl_b64 s[0:1], s[64:65], 11
	v_and_b32_e32 v1, 63, v215
	s_add_u32 s0, s20, s0
	v_lshlrev_b32_e32 v4, 4, v1
	v_mov_b32_e32 v5, 0
	s_addc_u32 s1, s21, s1
	v_lshl_add_u64 v[2:3], s[0:1], 0, v[4:5]
	s_mov_b64 s[0:1], 0x3100400
	s_ashr_i32 s63, s62, 31
	v_lshl_add_u64 v[2:3], v[2:3], 0, s[0:1]
	s_lshl_b64 s[0:1], s[62:63], 11
	s_lshl_b64 s[2:3], s[64:65], 12
	v_readlane_b32 s36, v251, 1
	v_readlane_b32 s37, v251, 2
	s_add_u32 s2, s36, s2
	v_lshlrev_b32_e32 v4, 5, v1
	s_addc_u32 s3, s37, s3
	v_lshl_add_u64 v[4:5], s[2:3], 0, v[4:5]
	s_mov_b64 s[2:3], 0x800
	v_lshl_add_u64 v[4:5], v[4:5], 0, s[2:3]
	s_lshl_b64 s[2:3], s[62:63], 12
	s_mov_b32 s5, s64
	v_readlane_b32 s38, v251, 3
	v_readlane_b32 s39, v251, 4
	v_readlane_b32 s40, v251, 5
	v_readlane_b32 s41, v251, 6
	v_readlane_b32 s42, v251, 7
	v_readlane_b32 s43, v251, 8
	v_readlane_b32 s44, v251, 9
	v_readlane_b32 s45, v251, 10
	v_readlane_b32 s46, v251, 11
	v_readlane_b32 s47, v251, 12
	v_readlane_b32 s48, v251, 13
	v_readlane_b32 s49, v251, 14
	v_readlane_b32 s50, v251, 15
	v_readlane_b32 s51, v251, 16
	global_load_dwordx4 v[116:119], v[4:5], off offset:-2048 nt
	global_load_dwordx4 v[120:123], v[4:5], off offset:-2032 nt
	global_load_dwordx4 v[124:127], v[4:5], off nt
	global_load_dwordx4 v[128:131], v[4:5], off offset:16 nt
	v_lshl_add_u64 v[4:5], v[4:5], 0, s[2:3]
	s_waitcnt vmcnt(0)
.LBB0_59:
	s_add_i32 s5, s5, s62
	s_cmpk_gt_i32 s5, 0x7fff
	s_waitcnt vmcnt(2)
	v_cvt_pk_bf16_f32 v6, v116, v117
	v_cvt_pk_bf16_f32 v7, v118, v119
	v_cvt_pk_bf16_f32 v8, v120, v121
	v_cvt_pk_bf16_f32 v9, v122, v123
	v_cvt_pk_bf16_f32 v10, v124, v125
	v_cvt_pk_bf16_f32 v11, v126, v127
	v_cvt_pk_bf16_f32 v12, v128, v129
	v_cvt_pk_bf16_f32 v13, v130, v131
	s_cbranch_scc1 .Lp0x_nopf
	global_load_dwordx4 v[116:119], v[4:5], off offset:-2048 nt
	global_load_dwordx4 v[120:123], v[4:5], off offset:-2032 nt
	global_load_dwordx4 v[124:127], v[4:5], off nt
	global_load_dwordx4 v[128:131], v[4:5], off offset:16 nt
	v_lshl_add_u64 v[4:5], v[4:5], 0, s[2:3]
.Lp0x_nopf:
	global_store_dwordx4 v[2:3], v[6:9], off offset:-1024
	global_store_dwordx4 v[2:3], v[10:13], off
	v_lshl_add_u64 v[2:3], v[2:3], 0, s[0:1]
	s_cbranch_scc0 .LBB0_59
